# SSD prompt loop output stage: the 8 serialized ds_read_u16 (each with its own lgkmcnt(0)) issued together after the intra MFMAs
# baseline (speedup 1.0000x reference)
; __device__ __forceinline__ float ex2(float x) { return __builtin_amdgcn_exp2f(x); }
; template <int DK, int MODE>
; __device__ void rec_prompt_item(const Params& p, const int item, unsigned char* smem) {
;     ...
; #pragma unroll KUNR
;     for (int ks = 0; ks < KS; ++ks) {
;       const bf16x8 a = *(const bf16x8*)(Qs + (16 * fi + l15) * QS + ks * 64 + g * 16);
;       bf16x8 bk[2], bs[2];
; #pragma unroll
;       for (int x = 0; x < 2; ++x) {
;         bk[x] = *(const bf16x8*)(Ks + (16 * (fe0 + x) + l15) * QS + ks * 64 + g * 16);
;         bs[x] = *(const bf16x8*)(STs + (16 * (fe0 + x) + l15) * QS + ks * 64 + g * 16);
;       }
; #pragma unroll
;       for (int x = 0; x < 2; ++x) {
;         sc[x] = __builtin_amdgcn_mfma_f32_16x16x32_bf16(a, bk[x], sc[x], 0, 0, 0);
;         cr[x] = __builtin_amdgcn_mfma_f32_16x16x32_bf16(a, bs[x], cr[x], 0, 0, 0);
;       }
;     }
;     float ci[4];
; #pragma unroll
;     for (int r = 0; r < 4; ++r) ci[r] = cumS[16 * fi + 4 * g + r];
; #pragma unroll
;     for (int x = 0; x < 2; ++x) {
;       const int fj = fe0 + x;
;       const int j = 16 * fj + l15;
;       const float cj = cumS[j], uj = uS[j];
; #pragma unroll
;       for (int r = 0; r < 4; ++r) {
;         const int i = 16 * fi + 4 * g + r;
;         float v = 0.f;
;         if (j <= i) v = sc[x][r] * ex2(ci[r] - cj) * uj;
;         *(u16*)(Ps + i * PS + j * 2) = f2bf(v);
;       }
;     }
;     {
;       const float atot = ex2(cumS[63]);
; #pragma unroll
;       for (int mf = 0; mf < MF; ++mf)
; #pragma unroll
;         for (int nf = 0; nf < 4; ++nf)
; #pragma unroll
;           for (int r = 0; r < 4; ++r) S[mf][nf][r] *= atot;
; #pragma unroll
;       for (int ks = 0; ks < 2; ++ks) {
;         bf16x8 af[MF], bfv[4];
; #pragma unroll
;         for (int mf = 0; mf < MF; ++mf) af[mf] = trfrag(Ks, QS, 32 * ks, dw + 16 * mf, lane);
; #pragma unroll
;         for (int nf = 0; nf < 4; ++nf) bfv[nf] = trfrag(Vts, VS, 32 * ks, 16 * nf, lane);
; #pragma unroll
;         for (int mf = 0; mf < MF; ++mf)
; #pragma unroll
;           for (int nf = 0; nf < 4; ++nf)
;             S[mf][nf] = __builtin_amdgcn_mfma_f32_16x16x32_bf16(af[mf], bfv[nf], S[mf][nf], 0, 0, 0);
;       }
;     }
.LBB0_1715:
	v_add_u32_e32 v235, v169, v167
	ds_read_b128 v[56:59], v191
	ds_read_b128 v[60:63], v192 offset:18432
	ds_read_b128 v[64:67], v192 offset:36864
	ds_read_b128 v[68:71], v193 offset:18432
	ds_read_b128 v[236:239], v193 offset:36864
	ds_read_b128 v[240:243], v191 offset:64
	ds_read_b128 v[244:247], v192 offset:18496
	ds_read_b128 v[248:251], v192 offset:36928
	ds_read_b128 v[144:147], v193 offset:18496
	s_waitcnt lgkmcnt(7)
	v_mfma_f32_16x16x32_bf16 v[60:63], v[56:59], v[60:63], 0
	s_waitcnt lgkmcnt(6)
	v_mfma_f32_16x16x32_bf16 v[64:67], v[56:59], v[64:67], 0
	s_waitcnt lgkmcnt(5)
	v_mfma_f32_16x16x32_bf16 v[68:71], v[56:59], v[68:71], 0
	s_waitcnt lgkmcnt(4)
	v_mfma_f32_16x16x32_bf16 v[56:59], v[56:59], v[236:239], 0
	ds_read_b128 v[236:239], v193 offset:36928
	s_waitcnt lgkmcnt(3)
	v_mfma_f32_16x16x32_bf16 v[60:63], v[240:243], v[244:247], v[60:63]
	ds_read_b128 v[244:247], v191 offset:128
	s_waitcnt lgkmcnt(3)
	v_mfma_f32_16x16x32_bf16 v[64:67], v[240:243], v[248:251], v[64:67]
	ds_read_b128 v[248:251], v192 offset:18560
	s_waitcnt lgkmcnt(3)
	v_mfma_f32_16x16x32_bf16 v[68:71], v[240:243], v[144:147], v[68:71]
	ds_read_b128 v[144:147], v192 offset:36992
	s_waitcnt lgkmcnt(3)
	v_mfma_f32_16x16x32_bf16 v[56:59], v[240:243], v[236:239], v[56:59]
	ds_read_b128 v[236:239], v193 offset:18560
	ds_read_b128 v[240:243], v193 offset:36992
	s_waitcnt lgkmcnt(3)
	v_mfma_f32_16x16x32_bf16 v[60:63], v[244:247], v[248:251], v[60:63]
	ds_read_b128 v[248:251], v191 offset:192
	s_waitcnt lgkmcnt(3)
	v_mfma_f32_16x16x32_bf16 v[64:67], v[244:247], v[144:147], v[64:67]
	ds_read_b128 v[144:147], v192 offset:37056
	s_waitcnt lgkmcnt(3)
	v_mfma_f32_16x16x32_bf16 v[68:71], v[244:247], v[236:239], v[68:71]
	ds_read_b128 v[236:239], v192 offset:18624
	s_waitcnt lgkmcnt(3)
	v_mfma_f32_16x16x32_bf16 v[56:59], v[244:247], v[240:243], v[56:59]
	ds_read_b128 v[240:243], v193 offset:18624
	ds_read_b128 v[244:247], v193 offset:37056
	s_waitcnt lgkmcnt(2)
	v_mfma_f32_16x16x32_bf16 v[236:239], v[248:251], v[236:239], v[60:63]
	v_mfma_f32_16x16x32_bf16 v[60:63], v[248:251], v[144:147], v[64:67]
	s_nop 2
	ds_read_b128 v[64:67], v195
	ds_read_b32 v135, v162
	ds_read_b32 v137, v163
	s_waitcnt lgkmcnt(1)
	v_sub_f32_e32 v139, v64, v135
	v_exp_f32_e32 v139, v139
	v_mfma_f32_16x16x32_bf16 v[68:71], v[248:251], v[240:243], v[68:71]
	v_mul_f32_e32 v139, v236, v139
	s_waitcnt lgkmcnt(0)
	v_mul_f32_e32 v139, v137, v139
	v_cvt_pk_bf16_f32 v139, v139, s0
	v_cndmask_b32_e64 v139, v139, 0, s[6:7]
	ds_write_b16 v196, v139
	v_sub_f32_e32 v139, v65, v135
	v_exp_f32_e32 v139, v139
	v_mfma_f32_16x16x32_bf16 v[56:59], v[248:251], v[244:247], v[56:59]
	v_mul_f32_e32 v139, v237, v139
	v_mul_f32_e32 v139, v137, v139
	v_cvt_pk_bf16_f32 v139, v139, s0
	v_cndmask_b32_e64 v139, v139, 0, s[8:9]
	ds_write_b16 v196, v139 offset:144
	v_sub_f32_e32 v139, v66, v135
	v_sub_f32_e32 v135, v67, v135
	v_exp_f32_e32 v139, v139
	v_exp_f32_e32 v135, v135
	v_mul_f32_e32 v139, v238, v139
	v_mul_f32_e32 v135, v239, v135
	v_mul_f32_e32 v139, v137, v139
	v_mul_f32_e32 v135, v137, v135
	v_cvt_pk_bf16_f32 v139, v139, s0
	v_cvt_pk_bf16_f32 v135, v135, s0
	v_cndmask_b32_e64 v139, v139, 0, s[10:11]
	v_cndmask_b32_e64 v135, v135, 0, s[12:13]
	ds_write_b16 v196, v139 offset:288
	ds_write_b16 v196, v135 offset:432
	ds_read_b32 v135, v164
	ds_read_b32 v137, v165
	s_waitcnt lgkmcnt(1)
	v_sub_f32_e32 v139, v64, v135
	v_exp_f32_e32 v139, v139
	s_nop 0
	v_mul_f32_e32 v68, v68, v139
	s_waitcnt lgkmcnt(0)
	v_mul_f32_e32 v68, v137, v68
	v_cvt_pk_bf16_f32 v68, v68, s0
	v_cndmask_b32_e64 v68, v68, 0, s[14:15]
	ds_write_b16 v197, v68
	v_sub_f32_e32 v68, v65, v135
	v_exp_f32_e32 v68, v68
	v_exp_f32_e32 v65, v65
	v_mul_f32_e32 v68, v69, v68
	v_mul_f32_e32 v68, v137, v68
	v_cvt_pk_bf16_f32 v68, v68, s0
	v_cndmask_b32_e64 v68, v68, 0, s[16:17]
	ds_write_b16 v197, v68 offset:144
	v_sub_f32_e32 v68, v66, v135
	v_exp_f32_e32 v68, v68
	v_exp_f32_e32 v66, v66
	v_mul_f32_e32 v68, v70, v68
	v_mul_f32_e32 v68, v137, v68
	v_cvt_pk_bf16_f32 v68, v68, s0
	v_cndmask_b32_e64 v68, v68, 0, s[18:19]
	ds_write_b16 v197, v68 offset:288
	v_sub_f32_e32 v68, v67, v135
	v_exp_f32_e32 v68, v68
	v_exp_f32_e32 v67, v67
	v_mul_f32_e32 v68, v71, v68
	v_mul_f32_e32 v68, v137, v68
	v_cvt_pk_bf16_f32 v68, v68, s0
	v_cndmask_b32_e64 v68, v68, 0, s[20:21]
	ds_write_b16 v197, v68 offset:432
	ds_read_b32 v68, v189
	s_waitcnt lgkmcnt(0)
	v_exp_f32_e32 v68, v68
	s_nop 0
	v_pk_mul_f32 v[54:55], v[54:55], v[68:69] op_sel_hi:[1,0]
	v_pk_mul_f32 v[52:53], v[52:53], v[68:69] op_sel_hi:[1,0]
	v_pk_mul_f32 v[50:51], v[50:51], v[68:69] op_sel_hi:[1,0]
	v_pk_mul_f32 v[48:49], v[48:49], v[68:69] op_sel_hi:[1,0]
	v_pk_mul_f32 v[46:47], v[46:47], v[68:69] op_sel_hi:[1,0]
	v_pk_mul_f32 v[44:45], v[44:45], v[68:69] op_sel_hi:[1,0]
	v_pk_mul_f32 v[42:43], v[42:43], v[68:69] op_sel_hi:[1,0]
	v_pk_mul_f32 v[40:41], v[40:41], v[68:69] op_sel_hi:[1,0]
	ds_read_b64_tr_b16 v[68:69], v198 offset:18432
	ds_read_b64_tr_b16 v[70:71], v198 offset:19584
	ds_read_b64_tr_b16 v[146:147], v199 offset:640
	ds_read_b64_tr_b16 v[144:145], v199
	ds_read_b64_tr_b16 v[236:237], v199 offset:32
	ds_read_b64_tr_b16 v[238:239], v199 offset:672
	ds_read_b64_tr_b16 v[240:241], v199 offset:64
	ds_read_b64_tr_b16 v[242:243], v199 offset:704
	ds_read_b64_tr_b16 v[244:245], v199 offset:96
	ds_read_b64_tr_b16 v[246:247], v199 offset:736
	s_waitcnt lgkmcnt(6)
	v_mfma_f32_16x16x32_bf16 v[52:55], v[68:71], v[144:147], v[52:55]
	s_waitcnt lgkmcnt(4)
	v_mfma_f32_16x16x32_bf16 v[48:51], v[68:71], v[236:239], v[48:51]
	s_waitcnt lgkmcnt(2)
	v_mfma_f32_16x16x32_bf16 v[144:147], v[68:71], v[240:243], v[44:47]
	s_waitcnt lgkmcnt(0)
	v_mfma_f32_16x16x32_bf16 v[68:71], v[68:71], v[244:247], v[40:43]
	ds_read_b64_tr_b16 v[236:237], v198 offset:27648
	ds_read_b64_tr_b16 v[238:239], v198 offset:28800
	s_nop 0
	ds_read_b64_tr_b16 v[40:41], v199 offset:5120
	ds_read_b64_tr_b16 v[42:43], v199 offset:5760
	ds_read_b64_tr_b16 v[44:45], v199 offset:5152
	ds_read_b64_tr_b16 v[46:47], v199 offset:5792
	ds_read_b64_tr_b16 v[240:241], v199 offset:5184
	ds_read_b64_tr_b16 v[242:243], v199 offset:5824
	ds_read_b64_tr_b16 v[244:245], v199 offset:5216
	ds_read_b64_tr_b16 v[246:247], v199 offset:5856
	s_waitcnt lgkmcnt(0)
	s_barrier
; __device__ __forceinline__ float bf2f(u16 h) { return __uint_as_float(((uint32_t)h) << 16); }
; __device__ __forceinline__ float ex2(float x) { return __builtin_amdgcn_exp2f(x); }
; __device__ __forceinline__ float silu(float x) { return x * __builtin_amdgcn_rcpf(1.0f + __expf(-x)); }
; template <int DK, int MODE>
; __device__ void rec_prompt_item(const Params& p, const int item, unsigned char* smem) {
;     ...
;     f32x4 in[2];
; #pragma unroll
;     for (int x = 0; x < 2; ++x) in[x] = (f32x4){0.f, 0.f, 0.f, 0.f};
; #pragma unroll
;     for (int ks = 0; ks < 2; ++ks) {
;       const bf16x8 a = *(const bf16x8*)(Ps + (16 * fi + l15) * PS + ks * 64 + g * 16);
;       bf16x8 bv[2];
; #pragma unroll
;       for (int x = 0; x < 2; ++x) bv[x] = trfrag(Vs, VS, 32 * ks, 16 * (fe0 + x), lane);
; #pragma unroll
;       for (int x = 0; x < 2; ++x) in[x] = __builtin_amdgcn_mfma_f32_16x16x32_bf16(a, bv[x], in[x], 0, 0, 0);
;     }
;     {
;       float ss[4] = {0.f, 0.f, 0.f, 0.f};
;       u16* aout = (u16*)(p.ws + OFF_A2);
;       float* parts = (float*)(p.ws + OFF_PARTS);
; #pragma unroll
;       for (int x = 0; x < 2; ++x) {
;         const int e = 16 * (fe0 + x) + l15;
;         const float gn = gnv[x];
;         const int ocol = (MODE == 0) ? (h * 512 + s * 64 + e) : (h * 64 + e);
; #pragma unroll
;         for (int r = 0; r < 4; ++r) {
;           const int i = 16 * fi + 4 * g + r;
;           float o = in[x][r] + cr[x][r] * ex2(ci[r]);
;           const float gv = bf2f(gzc[x][r]);
;           float val;
;           if (MODE == 0) {
;             ss[r] += o * o;
;             val = o * gn * silu(gv);
;           } else {
;             const float xs = bf2f(*(const u16*)(Vs + i * VS + e * 2));
;             const float y = o + xs * dsk;
;             const float gg = y * silu(gv);
;             ss[r] += gg * gg;
;             val = gg * gn;
;           }
;           *(u16*)((char*)aout + (size_t)r0 * 4096 + 32 * x + aoff[r]) = f2bf(val);
;         }
;       }
; #pragma unroll
;       for (int r = 0; r < 4; ++r) {
;         const float v = row16_sum(ss[r]);
;         if (l15 == 0) {
;           const int i = 16 * fi + 4 * g + r;
;           const int slot = (MODE == 0) ? (h * 16 + s * 2 + (w & 1)) : ((h >> 2) * 8 + (h & 3) * 2 + (w & 1));
;           parts[(size_t)(r0 + i) * 64 + slot] = v;
;         }
	v_mfma_f32_16x16x32_bf16 v[44:47], v[236:239], v[44:47], v[48:51]
	v_mfma_f32_16x16x32_bf16 v[48:51], v[236:239], v[244:247], v[68:71]
	s_nop 2
	ds_read_b128 v[68:71], v200
	v_mfma_f32_16x16x32_bf16 v[40:43], v[236:239], v[40:43], v[52:55]
	v_mfma_f32_16x16x32_bf16 v[52:55], v[236:239], v[240:243], v[144:147]
	v_add_u32_e32 v236, v166, v167
	v_add_u32_e32 v237, v166, v168
	s_nop 0
	ds_read_b64_tr_b16 v[144:145], v236 offset:55296
	ds_read_b64_tr_b16 v[146:147], v236 offset:55936
	ds_read_b64_tr_b16 v[238:239], v237 offset:55296
	ds_read_b64_tr_b16 v[240:241], v237 offset:55936
	s_waitcnt lgkmcnt(2)
	v_mfma_f32_16x16x32_bf16 v[144:147], v[68:71], v[144:147], 0
	s_waitcnt lgkmcnt(0)
	v_mfma_f32_16x16x32_bf16 v[68:71], v[68:71], v[238:241], 0
	ds_read_b128 v[240:243], v200 offset:64
	ds_read_b64_tr_b16 v[244:245], v235 offset:55296
	ds_read_b64_tr_b16 v[246:247], v235 offset:55936
	v_add_u32_e32 v238, v169, v168
	ds_read_b64_tr_b16 v[248:249], v238 offset:55296
	ds_read_b64_tr_b16 v[250:251], v238 offset:55936
	v_exp_f32_e32 v239, v64
	v_lshlrev_b32_e32 v64, 16, v134
	ds_read_u16 v134, v201 offset:55296
	s_waitcnt lgkmcnt(3)
	v_mfma_f32_16x16x32_bf16 v[144:147], v[240:243], v[244:247], v[144:147]
	s_waitcnt lgkmcnt(0)
	v_lshlrev_b32_e32 v134, 16, v134
	v_mfma_f32_16x16x32_bf16 v[68:71], v[240:243], v[248:251], v[68:71]
	ds_read_u16 v245, v201 offset:55456
	ds_read_u16 v246, v201 offset:55616
	ds_read_u16 v247, v201 offset:55776
	ds_read_u16 v248, v202 offset:55296
	ds_read_u16 v249, v202 offset:55456
	ds_read_u16 v250, v202 offset:55616
	ds_read_u16 v251, v202 offset:55776
	s_nop 4
	v_fma_f32 v60, v60, v239, v144
	v_fmac_f32_e32 v60, v74, v134
	v_mul_f32_e32 v134, 0xbfb8aa3b, v64
	v_exp_f32_e32 v134, v134
	v_fmac_f32_e32 v147, v63, v67
	v_fma_f32 v56, v56, v239, v68
	v_lshlrev_b32_e32 v68, 16, v234
	v_add_f32_e32 v134, 1.0, v134
	v_rcp_f32_e32 v134, v134
	v_fmac_f32_e32 v71, v59, v67
	v_mul_f32_e32 v64, v134, v64
	v_mul_f32_e32 v244, v64, v60
	v_lshl_add_u64 v[134:135], v[112:113], 0, s[24:25]
	v_mul_f32_e32 v60, v203, v244
	v_add_co_u32_e32 v240, vcc, s63, v134
	v_cvt_pk_bf16_f32 v60, v60, s0
	s_nop 0
	v_addc_co_u32_e32 v241, vcc, 0, v135, vcc
	global_store_short v[240:241], v60, off
	v_fma_f32 v60, v61, v65, v145
	v_lshlrev_b32_e32 v61, 16, v136
	s_waitcnt lgkmcnt(0)
	v_lshlrev_b32_e32 v64, 16, v245
	v_fmac_f32_e32 v60, v74, v64
	v_mul_f32_e32 v64, 0xbfb8aa3b, v61
	v_exp_f32_e32 v64, v64
	v_lshl_add_u64 v[136:137], v[108:109], 0, s[24:25]
	v_add_co_u32_e32 v144, vcc, s63, v136
	v_add_f32_e32 v64, 1.0, v64
	v_rcp_f32_e32 v64, v64
	v_addc_co_u32_e32 v145, vcc, 0, v137, vcc
	v_mul_f32_e32 v61, v64, v61
	v_mul_f32_e32 v64, v61, v60
	v_mul_f32_e32 v60, v203, v64
	v_cvt_pk_bf16_f32 v60, v60, s0
	global_store_short v[144:145], v60, off
	v_fma_f32 v60, v62, v66, v146
	v_lshlrev_b32_e32 v61, 16, v138
	v_lshl_add_u64 v[138:139], v[102:103], 0, s[24:25]
	v_add_co_u32_e32 v242, vcc, s63, v138
	v_lshlrev_b32_e32 v62, 16, v246
	v_fmac_f32_e32 v60, v74, v62
	v_mul_f32_e32 v62, 0xbfb8aa3b, v61
	v_exp_f32_e32 v62, v62
	v_addc_co_u32_e32 v243, vcc, 0, v139, vcc
	v_add_f32_e32 v62, 1.0, v62
	v_rcp_f32_e32 v62, v62
	s_nop 0
	v_mul_f32_e32 v61, v62, v61
	v_mul_f32_e32 v62, v61, v60
	v_mul_f32_e32 v60, v203, v62
	v_cvt_pk_bf16_f32 v60, v60, s0
	global_store_short v[242:243], v60, off
	v_lshlrev_b32_e32 v60, 16, v140
	v_lshlrev_b32_e32 v61, 16, v247
	v_fmac_f32_e32 v147, v74, v61
	v_mul_f32_e32 v61, 0xbfb8aa3b, v60
	v_exp_f32_e32 v61, v61
	v_lshl_add_u64 v[140:141], v[94:95], 0, s[24:25]
	v_add_f32_e32 v61, 1.0, v61
	v_rcp_f32_e32 v61, v61
	s_nop 0
	v_mul_f32_e32 v60, v61, v60
	v_mul_f32_e32 v63, v60, v147
	v_mul_f32_e32 v60, v203, v63
	v_cvt_pk_bf16_f32 v146, v60, s0
	v_add_co_u32_e32 v60, vcc, s63, v140
	s_nop 1
	v_addc_co_u32_e32 v61, vcc, 0, v141, vcc
	global_store_short v[60:61], v146, off
	v_lshlrev_b32_e32 v146, 16, v248
	v_fmac_f32_e32 v56, v74, v146
	v_mul_f32_e32 v146, 0xbfb8aa3b, v68
	v_exp_f32_e32 v146, v146
	s_nop 0
	v_add_f32_e32 v146, 1.0, v146
	v_rcp_f32_e32 v146, v146
	s_nop 0
	v_mul_f32_e32 v68, v146, v68
	v_mul_f32_e32 v56, v68, v56
	v_mul_f32_e32 v68, v56, v56
	v_mul_f32_e32 v56, v204, v56
	v_cvt_pk_bf16_f32 v56, v56, s0
	global_store_short v[240:241], v56, off offset:32
	v_fma_f32 v56, v57, v65, v69
	v_lshlrev_b32_e32 v57, 16, v233
	v_fmac_f32_e32 v68, v244, v244
	v_lshlrev_b32_e32 v65, 16, v249
	v_fmac_f32_e32 v56, v74, v65
	v_mul_f32_e32 v65, 0xbfb8aa3b, v57
	v_exp_f32_e32 v65, v65
	s_nop 0
	v_add_f32_e32 v65, 1.0, v65
	v_rcp_f32_e32 v65, v65
	s_nop 0
	v_mul_f32_e32 v57, v65, v57
	v_mul_f32_e32 v65, v57, v56
	v_mul_f32_e32 v56, v204, v65
	v_cvt_pk_bf16_f32 v56, v56, s0
	global_store_short v[144:145], v56, off offset:32
	v_fma_f32 v56, v58, v66, v70
	v_lshlrev_b32_e32 v57, 16, v232
	v_lshlrev_b32_e32 v58, 16, v250
	v_fmac_f32_e32 v56, v74, v58
	v_mul_f32_e32 v58, 0xbfb8aa3b, v57
	v_exp_f32_e32 v58, v58
	s_nop 0
	v_add_f32_e32 v58, 1.0, v58
	v_rcp_f32_e32 v58, v58
	s_nop 0
	v_mul_f32_e32 v57, v58, v57
	v_mul_f32_e32 v58, v57, v56
	v_mul_f32_e32 v56, v204, v58
	v_cvt_pk_bf16_f32 v56, v56, s0
	global_store_short v[242:243], v56, off offset:32
	v_lshlrev_b32_e32 v56, 16, v231
	v_lshlrev_b32_e32 v57, 16, v251
	v_fmac_f32_e32 v71, v74, v57
	v_mul_f32_e32 v57, 0xbfb8aa3b, v56
	v_exp_f32_e32 v57, v57
	s_nop 0
	v_add_f32_e32 v57, 1.0, v57
	v_rcp_f32_e32 v57, v57
	s_nop 0
	v_mul_f32_e32 v56, v57, v56
	v_mul_f32_e32 v59, v56, v71
	v_mul_f32_e32 v56, v204, v59
	v_cvt_pk_bf16_f32 v56, v56, s0
	global_store_short v[60:61], v56, off offset:32
	s_nop 0
	v_add_f32_dpp v56, v68, v68 quad_perm:[1,0,3,2] row_mask:0xf bank_mask:0xf bound_ctrl:1
	s_nop 1
	v_add_f32_dpp v56, v56, v56 quad_perm:[2,3,0,1] row_mask:0xf bank_mask:0xf bound_ctrl:1
	s_nop 1
	v_add_f32_dpp v60, v56, v56 row_ror:4 row_mask:0xf bank_mask:0xf bound_ctrl:1
	v_lshl_add_u64 v[56:57], v[114:115], 0, s[24:25]
	s_nop 0
	v_mov_b32_dpp v61, v60 row_ror:8 row_mask:0xf bank_mask:0xf bound_ctrl:1
	s_and_saveexec_b64 s[48:49], s[4:5]
	s_cbranch_execz .LBB0_1717
	v_add_f32_e32 v60, v60, v61
	global_store_dword v[56:57], v60, off offset:-512

; __device__ __forceinline__ float ex2(float x) { return __builtin_amdgcn_exp2f(x); }
; template <int DK, int MODE>
; __device__ void rec_prompt_item(const Params& p, const int item, unsigned char* smem) {
;     ...
; #pragma unroll KUNR
;     for (int ks = 0; ks < KS; ++ks) {
;       const bf16x8 a = *(const bf16x8*)(Qs + (16 * fi + l15) * QS + ks * 64 + g * 16);
;       bf16x8 bk[2], bs[2];
; #pragma unroll
;       for (int x = 0; x < 2; ++x) {
;         bk[x] = *(const bf16x8*)(Ks + (16 * (fe0 + x) + l15) * QS + ks * 64 + g * 16);
;         bs[x] = *(const bf16x8*)(STs + (16 * (fe0 + x) + l15) * QS + ks * 64 + g * 16);
;       }
; #pragma unroll
;       for (int x = 0; x < 2; ++x) {
;         sc[x] = __builtin_amdgcn_mfma_f32_16x16x32_bf16(a, bk[x], sc[x], 0, 0, 0);
;         cr[x] = __builtin_amdgcn_mfma_f32_16x16x32_bf16(a, bs[x], cr[x], 0, 0, 0);
;       }
;     }
;     float ci[4];
; #pragma unroll
;     for (int r = 0; r < 4; ++r) ci[r] = cumS[16 * fi + 4 * g + r];
; #pragma unroll
;     for (int x = 0; x < 2; ++x) {
;       const int fj = fe0 + x;
;       const int j = 16 * fj + l15;
;       const float cj = cumS[j], uj = uS[j];
; #pragma unroll
;       for (int r = 0; r < 4; ++r) {
;         const int i = 16 * fi + 4 * g + r;
;         float v = 0.f;
;         if (j <= i) v = sc[x][r] * ex2(ci[r] - cj) * uj;
;         *(u16*)(Ps + i * PS + j * 2) = f2bf(v);
;       }
;     }
;     {
;       const float atot = ex2(cumS[63]);
; #pragma unroll
;       for (int mf = 0; mf < MF; ++mf)
; #pragma unroll
;         for (int nf = 0; nf < 4; ++nf)
; #pragma unroll
;           for (int r = 0; r < 4; ++r) S[mf][nf][r] *= atot;
; #pragma unroll
;       for (int ks = 0; ks < 2; ++ks) {
;         bf16x8 af[MF], bfv[4];
; #pragma unroll
;         for (int mf = 0; mf < MF; ++mf) af[mf] = trfrag(Ks, QS, 32 * ks, dw + 16 * mf, lane);
; #pragma unroll
;         for (int nf = 0; nf < 4; ++nf) bfv[nf] = trfrag(Vts, VS, 32 * ks, 16 * nf, lane);
; #pragma unroll
;         for (int mf = 0; mf < MF; ++mf)
; #pragma unroll
;           for (int nf = 0; nf < 4; ++nf)
;             S[mf][nf] = __builtin_amdgcn_mfma_f32_16x16x32_bf16(af[mf], bfv[nf], S[mf][nf], 0, 0, 0);
;       }
;     }
.LBB0_1727:
	ds_read_b128 v[56:59], v191
	ds_read_b128 v[60:63], v192 offset:18432
	ds_read_b128 v[64:67], v192 offset:36864
	ds_read_b128 v[68:71], v193 offset:18432
	ds_read_b128 v[124:127], v193 offset:36864
	ds_read_b128 v[120:123], v191 offset:64
	ds_read_b128 v[128:131], v192 offset:18496
	ds_read_b128 v[144:147], v192 offset:36928
	ds_read_b128 v[244:247], v193 offset:18496
	s_waitcnt lgkmcnt(7)
	v_mfma_f32_16x16x32_bf16 v[60:63], v[56:59], v[60:63], 0
	s_waitcnt lgkmcnt(6)
	v_mfma_f32_16x16x32_bf16 v[64:67], v[56:59], v[64:67], 0
	s_waitcnt lgkmcnt(5)
	v_mfma_f32_16x16x32_bf16 v[68:71], v[56:59], v[68:71], 0
	s_waitcnt lgkmcnt(4)
	v_mfma_f32_16x16x32_bf16 v[56:59], v[56:59], v[124:127], 0
	ds_read_b128 v[124:127], v193 offset:36928
	s_waitcnt lgkmcnt(3)
	v_mfma_f32_16x16x32_bf16 v[60:63], v[120:123], v[128:131], v[60:63]
	ds_read_b128 v[128:131], v191 offset:128
	s_waitcnt lgkmcnt(3)
	v_mfma_f32_16x16x32_bf16 v[64:67], v[120:123], v[144:147], v[64:67]
	ds_read_b128 v[144:147], v192 offset:18560
	s_waitcnt lgkmcnt(3)
	v_mfma_f32_16x16x32_bf16 v[68:71], v[120:123], v[244:247], v[68:71]
	ds_read_b128 v[244:247], v192 offset:36992
	s_waitcnt lgkmcnt(3)
	v_mfma_f32_16x16x32_bf16 v[56:59], v[120:123], v[124:127], v[56:59]
	ds_read_b128 v[124:127], v193 offset:18560
	ds_read_b128 v[120:123], v193 offset:36992
	s_waitcnt lgkmcnt(3)
	v_mfma_f32_16x16x32_bf16 v[60:63], v[128:131], v[144:147], v[60:63]
	ds_read_b128 v[144:147], v191 offset:192
	s_waitcnt lgkmcnt(3)
	v_mfma_f32_16x16x32_bf16 v[64:67], v[128:131], v[244:247], v[64:67]
	ds_read_b128 v[244:247], v192 offset:37056
	s_waitcnt lgkmcnt(3)
	v_mfma_f32_16x16x32_bf16 v[68:71], v[128:131], v[124:127], v[68:71]
	ds_read_b128 v[124:127], v192 offset:18624
	s_waitcnt lgkmcnt(3)
	v_mfma_f32_16x16x32_bf16 v[56:59], v[128:131], v[120:123], v[56:59]
	ds_read_b128 v[120:123], v193 offset:18624
	ds_read_b128 v[128:131], v193 offset:37056
	s_waitcnt lgkmcnt(2)
	v_mfma_f32_16x16x32_bf16 v[124:127], v[144:147], v[124:127], v[60:63]
	v_mfma_f32_16x16x32_bf16 v[60:63], v[144:147], v[244:247], v[64:67]
	s_waitcnt lgkmcnt(1)
	v_mfma_f32_16x16x32_bf16 v[68:71], v[144:147], v[120:123], v[68:71]
	s_waitcnt lgkmcnt(0)
	v_mfma_f32_16x16x32_bf16 v[56:59], v[144:147], v[128:131], v[56:59]
	ds_read_b128 v[64:67], v195
	ds_read_b32 v120, v162
	ds_read_b32 v121, v163
	s_waitcnt lgkmcnt(1)
	v_sub_f32_e32 v122, v64, v120
	v_exp_f32_e32 v122, v122
	s_nop 0
	v_mul_f32_e32 v122, v124, v122
	s_waitcnt lgkmcnt(0)
	v_mul_f32_e32 v122, v121, v122
	v_cvt_pk_bf16_f32 v122, v122, s0
	v_cndmask_b32_e64 v122, v122, 0, s[6:7]
	ds_write_b16 v196, v122
	v_sub_f32_e32 v122, v65, v120
	v_exp_f32_e32 v122, v122
	s_nop 0
	v_mul_f32_e32 v122, v125, v122
	v_mul_f32_e32 v122, v121, v122
	v_cvt_pk_bf16_f32 v122, v122, s0
	v_cndmask_b32_e64 v122, v122, 0, s[8:9]
	ds_write_b16 v196, v122 offset:144
	v_sub_f32_e32 v122, v66, v120
	v_sub_f32_e32 v120, v67, v120
	v_exp_f32_e32 v122, v122
	v_exp_f32_e32 v120, v120
	v_mul_f32_e32 v122, v126, v122
	v_mul_f32_e32 v120, v127, v120
	v_mul_f32_e32 v122, v121, v122
	v_mul_f32_e32 v120, v121, v120
	v_cvt_pk_bf16_f32 v122, v122, s0
	v_cvt_pk_bf16_f32 v120, v120, s0
	v_cndmask_b32_e64 v122, v122, 0, s[10:11]
	v_cndmask_b32_e64 v120, v120, 0, s[12:13]
	ds_write_b16 v196, v122 offset:288
	ds_write_b16 v196, v120 offset:432
	ds_read_b32 v120, v164
	ds_read_b32 v121, v165
	s_waitcnt lgkmcnt(1)
	v_sub_f32_e32 v122, v64, v120
	v_exp_f32_e32 v122, v122
	s_nop 0
	v_mul_f32_e32 v68, v68, v122
	s_waitcnt lgkmcnt(0)
	v_mul_f32_e32 v68, v121, v68
	v_cvt_pk_bf16_f32 v68, v68, s0
	v_cndmask_b32_e64 v68, v68, 0, s[14:15]
	ds_write_b16 v197, v68
	v_sub_f32_e32 v68, v65, v120
	v_exp_f32_e32 v68, v68
	v_exp_f32_e32 v65, v65
	v_mul_f32_e32 v68, v69, v68
	v_mul_f32_e32 v68, v121, v68
	v_cvt_pk_bf16_f32 v68, v68, s0
	v_cndmask_b32_e64 v68, v68, 0, s[16:17]
	ds_write_b16 v197, v68 offset:144
	v_sub_f32_e32 v68, v66, v120
	v_exp_f32_e32 v68, v68
	v_exp_f32_e32 v66, v66
	v_mul_f32_e32 v68, v70, v68
	v_mul_f32_e32 v68, v121, v68
	v_cvt_pk_bf16_f32 v68, v68, s0
	v_cndmask_b32_e64 v68, v68, 0, s[18:19]
	ds_write_b16 v197, v68 offset:288
	v_sub_f32_e32 v68, v67, v120
	v_exp_f32_e32 v68, v68
	v_exp_f32_e32 v67, v67
	v_mul_f32_e32 v68, v71, v68
	v_mul_f32_e32 v68, v121, v68
	v_cvt_pk_bf16_f32 v68, v68, s0
	v_cndmask_b32_e64 v68, v68, 0, s[20:21]
	ds_write_b16 v197, v68 offset:432
	ds_read_b32 v68, v189
	s_waitcnt lgkmcnt(0)
	v_exp_f32_e32 v68, v68
	s_nop 0
	v_pk_mul_f32 v[42:43], v[42:43], v[68:69] op_sel_hi:[1,0]
	v_pk_mul_f32 v[40:41], v[40:41], v[68:69] op_sel_hi:[1,0]
	v_pk_mul_f32 v[46:47], v[46:47], v[68:69] op_sel_hi:[1,0]
	v_pk_mul_f32 v[44:45], v[44:45], v[68:69] op_sel_hi:[1,0]
	v_pk_mul_f32 v[54:55], v[54:55], v[68:69] op_sel_hi:[1,0]
	v_pk_mul_f32 v[52:53], v[52:53], v[68:69] op_sel_hi:[1,0]
	v_pk_mul_f32 v[50:51], v[50:51], v[68:69] op_sel_hi:[1,0]
	v_pk_mul_f32 v[48:49], v[48:49], v[68:69] op_sel_hi:[1,0]
	ds_read_b64_tr_b16 v[68:69], v198 offset:18432
	ds_read_b64_tr_b16 v[70:71], v198 offset:19584
	ds_read_b64_tr_b16 v[122:123], v199 offset:640
	ds_read_b64_tr_b16 v[120:121], v199
	ds_read_b64_tr_b16 v[124:125], v199 offset:32
	ds_read_b64_tr_b16 v[126:127], v199 offset:672
	ds_read_b64_tr_b16 v[128:129], v199 offset:64
	ds_read_b64_tr_b16 v[130:131], v199 offset:704
	ds_read_b64_tr_b16 v[144:145], v199 offset:96
	ds_read_b64_tr_b16 v[146:147], v199 offset:736
	s_waitcnt lgkmcnt(6)
	v_mfma_f32_16x16x32_bf16 v[40:43], v[68:71], v[120:123], v[40:43]
	s_waitcnt lgkmcnt(4)
	v_mfma_f32_16x16x32_bf16 v[44:47], v[68:71], v[124:127], v[44:47]
	s_waitcnt lgkmcnt(2)
	v_mfma_f32_16x16x32_bf16 v[120:123], v[68:71], v[128:131], v[52:55]
	s_waitcnt lgkmcnt(0)
	v_mfma_f32_16x16x32_bf16 v[68:71], v[68:71], v[144:147], v[48:51]
	ds_read_b64_tr_b16 v[124:125], v198 offset:27648
	ds_read_b64_tr_b16 v[126:127], v198 offset:28800
	s_nop 0
	ds_read_b64_tr_b16 v[48:49], v199 offset:5120
	ds_read_b64_tr_b16 v[50:51], v199 offset:5760
	ds_read_b64_tr_b16 v[128:129], v199 offset:5152
	ds_read_b64_tr_b16 v[130:131], v199 offset:5792
	ds_read_b64_tr_b16 v[144:145], v199 offset:5184
	ds_read_b64_tr_b16 v[146:147], v199 offset:5824
	ds_read_b64_tr_b16 v[244:245], v199 offset:5216
	ds_read_b64_tr_b16 v[246:247], v199 offset:5856
	s_waitcnt lgkmcnt(0)
	s_barrier
; __device__ __forceinline__ float bf2f(u16 h) { return __uint_as_float(((uint32_t)h) << 16); }
; __device__ __forceinline__ float ex2(float x) { return __builtin_amdgcn_exp2f(x); }
; __device__ __forceinline__ float silu(float x) { return x * __builtin_amdgcn_rcpf(1.0f + __expf(-x)); }
; template <int DK, int MODE>
; __device__ void rec_prompt_item(const Params& p, const int item, unsigned char* smem) {
;     ...
;     f32x4 in[2];
; #pragma unroll
;     for (int x = 0; x < 2; ++x) in[x] = (f32x4){0.f, 0.f, 0.f, 0.f};
; #pragma unroll
;     for (int ks = 0; ks < 2; ++ks) {
;       const bf16x8 a = *(const bf16x8*)(Ps + (16 * fi + l15) * PS + ks * 64 + g * 16);
;       bf16x8 bv[2];
; #pragma unroll
;       for (int x = 0; x < 2; ++x) bv[x] = trfrag(Vs, VS, 32 * ks, 16 * (fe0 + x), lane);
; #pragma unroll
;       for (int x = 0; x < 2; ++x) in[x] = __builtin_amdgcn_mfma_f32_16x16x32_bf16(a, bv[x], in[x], 0, 0, 0);
;     }
;     {
;       float ss[4] = {0.f, 0.f, 0.f, 0.f};
;       u16* aout = (u16*)(p.ws + OFF_A2);
;       float* parts = (float*)(p.ws + OFF_PARTS);
; #pragma unroll
;       for (int x = 0; x < 2; ++x) {
;         const int e = 16 * (fe0 + x) + l15;
;         const float gn = gnv[x];
;         const int ocol = (MODE == 0) ? (h * 512 + s * 64 + e) : (h * 64 + e);
; #pragma unroll
;         for (int r = 0; r < 4; ++r) {
;           const int i = 16 * fi + 4 * g + r;
;           float o = in[x][r] + cr[x][r] * ex2(ci[r]);
;           const float gv = bf2f(gzc[x][r]);
;           float val;
;           if (MODE == 0) {
;             ss[r] += o * o;
;             val = o * gn * silu(gv);
;           } else {
;             const float xs = bf2f(*(const u16*)(Vs + i * VS + e * 2));
;             const float y = o + xs * dsk;
;             const float gg = y * silu(gv);
;             ss[r] += gg * gg;
;             val = gg * gn;
;           }
;           *(u16*)((char*)aout + (size_t)r0 * 4096 + 32 * x + aoff[r]) = f2bf(val);
;         }
;       }
; #pragma unroll
;       for (int r = 0; r < 4; ++r) {
;         const float v = row16_sum(ss[r]);
;         if (l15 == 0) {
;           const int i = 16 * fi + 4 * g + r;
;           const int slot = (MODE == 0) ? (h * 16 + s * 2 + (w & 1)) : ((h >> 2) * 8 + (h & 3) * 2 + (w & 1));
;           parts[(size_t)(r0 + i) * 64 + slot] = v;
;         }
	v_mfma_f32_16x16x32_bf16 v[52:55], v[124:127], v[48:51], v[40:43]
	v_mfma_f32_16x16x32_bf16 v[48:51], v[124:127], v[128:131], v[44:47]
	v_mfma_f32_16x16x32_bf16 v[44:47], v[124:127], v[144:147], v[120:123]
	v_mfma_f32_16x16x32_bf16 v[40:43], v[124:127], v[244:247], v[68:71]
	s_nop 2
	ds_read_b128 v[68:71], v200
	ds_read_b64_tr_b16 v[120:121], v236 offset:55296
	ds_read_b64_tr_b16 v[122:123], v236 offset:55936
	ds_read_b64_tr_b16 v[124:125], v237 offset:55296
	ds_read_b64_tr_b16 v[126:127], v237 offset:55936
	s_waitcnt lgkmcnt(2)
	v_mfma_f32_16x16x32_bf16 v[120:123], v[68:71], v[120:123], 0
	s_waitcnt lgkmcnt(0)
	v_mfma_f32_16x16x32_bf16 v[68:71], v[68:71], v[124:127], 0
	ds_read_b128 v[124:127], v200 offset:64
	ds_read_b64_tr_b16 v[128:129], v235 offset:55296
	ds_read_b64_tr_b16 v[130:131], v235 offset:55936
	ds_read_b64_tr_b16 v[144:145], v238 offset:55296
	ds_read_b64_tr_b16 v[146:147], v238 offset:55936
	s_waitcnt lgkmcnt(2)
	v_mfma_f32_16x16x32_bf16 v[120:123], v[124:127], v[128:131], v[120:123]
	v_exp_f32_e32 v128, v64
	v_lshlrev_b32_e32 v64, 16, v230
	s_waitcnt lgkmcnt(0)
	v_mfma_f32_16x16x32_bf16 v[68:71], v[124:127], v[144:147], v[68:71]
	v_add_co_u32_e32 v124, vcc, s67, v134
	s_nop 2
	v_fma_f32 v60, v60, v128, v120
	ds_read_u16 v120, v201 offset:55296
	ds_read_u16 v245, v201 offset:55456
	ds_read_u16 v246, v201 offset:55616
	ds_read_u16 v247, v201 offset:55776
	ds_read_u16 v248, v202 offset:55296
	ds_read_u16 v249, v202 offset:55456
	ds_read_u16 v250, v202 offset:55616
	ds_read_u16 v251, v202 offset:55776
	v_addc_co_u32_e32 v125, vcc, 0, v135, vcc
	v_fmac_f32_e32 v123, v63, v67
	v_fma_f32 v56, v56, v128, v68
	s_waitcnt lgkmcnt(0)
	v_lshlrev_b32_e32 v120, 16, v120
	v_fmac_f32_e32 v60, v74, v120
	v_mul_f32_e32 v120, 0xbfb8aa3b, v64
	v_exp_f32_e32 v120, v120
	v_lshlrev_b32_e32 v68, 16, v218
	v_fmac_f32_e32 v71, v59, v67
	v_add_f32_e32 v120, 1.0, v120
	v_rcp_f32_e32 v120, v120
	s_nop 0
	v_mul_f32_e32 v64, v120, v64
	v_mul_f32_e32 v129, v64, v60
	v_mul_f32_e32 v60, v203, v129
	v_cvt_pk_bf16_f32 v60, v60, s0
	global_store_short v[124:125], v60, off
	v_fma_f32 v60, v61, v65, v121
	v_lshlrev_b32_e32 v61, 16, v229
	v_lshlrev_b32_e32 v64, 16, v245
	v_fmac_f32_e32 v60, v74, v64
	v_mul_f32_e32 v64, 0xbfb8aa3b, v61
	v_exp_f32_e32 v64, v64
	v_add_co_u32_e32 v120, vcc, s67, v136
	v_add_f32_e32 v64, 1.0, v64
	v_rcp_f32_e32 v64, v64
	v_addc_co_u32_e32 v121, vcc, 0, v137, vcc
	v_add_co_u32_e32 v126, vcc, s67, v138
	v_mul_f32_e32 v61, v64, v61
	v_mul_f32_e32 v64, v61, v60
	v_mul_f32_e32 v60, v203, v64
	v_cvt_pk_bf16_f32 v60, v60, s0
	global_store_short v[120:121], v60, off
	v_fma_f32 v60, v62, v66, v122
	v_lshlrev_b32_e32 v61, 16, v228
	v_addc_co_u32_e32 v127, vcc, 0, v139, vcc
	v_lshlrev_b32_e32 v62, 16, v246
	v_fmac_f32_e32 v60, v74, v62
	v_mul_f32_e32 v62, 0xbfb8aa3b, v61
	v_exp_f32_e32 v62, v62
	s_nop 0
	v_add_f32_e32 v62, 1.0, v62
	v_rcp_f32_e32 v62, v62
	s_nop 0
	v_mul_f32_e32 v61, v62, v61
	v_mul_f32_e32 v62, v61, v60
	v_mul_f32_e32 v60, v203, v62
	v_cvt_pk_bf16_f32 v60, v60, s0
	global_store_short v[126:127], v60, off
	v_lshlrev_b32_e32 v60, 16, v219
	v_lshlrev_b32_e32 v61, 16, v247
	v_fmac_f32_e32 v123, v74, v61
	v_mul_f32_e32 v61, 0xbfb8aa3b, v60
	v_exp_f32_e32 v61, v61
	s_nop 0
	v_add_f32_e32 v61, 1.0, v61
	v_rcp_f32_e32 v61, v61
	s_nop 0
	v_mul_f32_e32 v60, v61, v60
	v_mul_f32_e32 v63, v60, v123
	v_mul_f32_e32 v60, v203, v63
	v_cvt_pk_bf16_f32 v122, v60, s0
	v_add_co_u32_e32 v60, vcc, s67, v140
	s_nop 1
	v_addc_co_u32_e32 v61, vcc, 0, v141, vcc
	global_store_short v[60:61], v122, off
	v_lshlrev_b32_e32 v122, 16, v248
	v_fmac_f32_e32 v56, v74, v122
	v_mul_f32_e32 v122, 0xbfb8aa3b, v68
	v_exp_f32_e32 v122, v122
	s_nop 0
	v_add_f32_e32 v122, 1.0, v122
	v_rcp_f32_e32 v122, v122
	s_nop 0
	v_mul_f32_e32 v68, v122, v68
	v_mul_f32_e32 v56, v68, v56
	v_mul_f32_e32 v68, v56, v56
	v_mul_f32_e32 v56, v204, v56
	v_cvt_pk_bf16_f32 v56, v56, s0
	global_store_short v[124:125], v56, off offset:32
	v_fma_f32 v56, v57, v65, v69
	v_lshlrev_b32_e32 v57, 16, v217
	v_fmac_f32_e32 v68, v129, v129
	v_lshlrev_b32_e32 v65, 16, v249
	v_fmac_f32_e32 v56, v74, v65
	v_mul_f32_e32 v65, 0xbfb8aa3b, v57
	v_exp_f32_e32 v65, v65
	s_nop 0
	v_add_f32_e32 v65, 1.0, v65
	v_rcp_f32_e32 v65, v65
	s_nop 0
	v_mul_f32_e32 v57, v65, v57
	v_mul_f32_e32 v65, v57, v56
	v_mul_f32_e32 v56, v204, v65
	v_cvt_pk_bf16_f32 v56, v56, s0
	global_store_short v[120:121], v56, off offset:32
	v_fma_f32 v56, v58, v66, v70
	v_lshlrev_b32_e32 v57, 16, v216
	v_lshlrev_b32_e32 v58, 16, v250
	v_fmac_f32_e32 v56, v74, v58
	v_mul_f32_e32 v58, 0xbfb8aa3b, v57
	v_exp_f32_e32 v58, v58
	s_nop 0
	v_add_f32_e32 v58, 1.0, v58
	v_rcp_f32_e32 v58, v58
	s_nop 0
	v_mul_f32_e32 v57, v58, v57
	v_mul_f32_e32 v58, v57, v56
	v_mul_f32_e32 v56, v204, v58
	v_cvt_pk_bf16_f32 v56, v56, s0
	global_store_short v[126:127], v56, off offset:32
	v_lshlrev_b32_e32 v56, 16, v215
	v_lshlrev_b32_e32 v57, 16, v251
	v_fmac_f32_e32 v71, v74, v57
	v_mul_f32_e32 v57, 0xbfb8aa3b, v56
	v_exp_f32_e32 v57, v57
	s_nop 0
	v_add_f32_e32 v57, 1.0, v57
	v_rcp_f32_e32 v57, v57
	s_nop 0
	v_mul_f32_e32 v56, v57, v56
	v_mul_f32_e32 v59, v56, v71
	v_mul_f32_e32 v56, v204, v59
	v_cvt_pk_bf16_f32 v56, v56, s0
	global_store_short v[60:61], v56, off offset:32
	s_nop 0
	v_add_f32_dpp v56, v68, v68 quad_perm:[1,0,3,2] row_mask:0xf bank_mask:0xf bound_ctrl:1
	s_nop 1
	v_add_f32_dpp v56, v56, v56 quad_perm:[2,3,0,1] row_mask:0xf bank_mask:0xf bound_ctrl:1
	s_nop 1
	v_add_f32_dpp v60, v56, v56 row_ror:4 row_mask:0xf bank_mask:0xf bound_ctrl:1
	v_lshl_add_u64 v[56:57], v[110:111], 0, s[24:25]
	s_nop 0
	v_mov_b32_dpp v61, v60 row_ror:8 row_mask:0xf bank_mask:0xf bound_ctrl:1
	s_and_saveexec_b64 s[46:47], s[4:5]
	s_cbranch_execz .LBB0_1729
	v_add_f32_e32 v60, v60, v61
	global_store_dword v[56:57], v60, off offset:-512
